# seams 2-9: the arrival atomic returns its ticket and the last local arriver itself does the XCD's writeback and cross-XCD arrival (no designated leader polling the per-XCD counter: one poll round trip
# baseline (speedup 1.0000x reference)
; __device__ __forceinline__ int lane_id_asm() { int l; asm volatile("v_mbcnt_lo_u32_b32 %0, -1, 0\n\tv_mbcnt_hi_u32_b32 %0, -1, %0" : "=v"(l)); return l; }
; __device__ __forceinline__ unsigned xb_ld(unsigned* p)              { return __hip_atomic_load(p, __ATOMIC_RELAXED, __HIP_MEMORY_SCOPE_AGENT); }
; __device__ __forceinline__ unsigned xb_add(unsigned* p, unsigned v) { return __hip_atomic_fetch_add(p, v, __ATOMIC_RELAXED, __HIP_MEMORY_SCOPE_AGENT); }
; #define XB_SPIN(cond, bar) do { unsigned _sp = 0; while (cond) { __builtin_amdgcn_s_sleep(1); \
;     if ((++_sp & 255u) == 0u) { if (xb_ld(&(bar)[XB_TMO])) break; if (_sp > XB_SPIN_CAP) { atomicAdd(&(bar)[XB_TMO], 1u); break; } } } } while (0)
; __device__ __forceinline__ void xcd_barrier(const XcdBarrier& b, const int wid) {
;     asm volatile("s_waitcnt vmcnt(0)" ::: "memory");
;     __syncthreads();
;     if (wid == 0 && lane_id_asm() == 0) {
;         unsigned* bar = b.bar;
;         __builtin_amdgcn_s_waitcnt(0);
;         unsigned nloc = b.st[0], nx = b.st[1];
;         if (nloc == 0u) { xcd_barrier_complete(bar, b.x, nloc, nx); b.st[0] = nloc; b.st[1] = nx; }
;         const unsigned old = xb_add(&bar[XB_XSUB(b.x)], 1u);
;         const unsigned gen = old / nloc;
;         if (old + 1u == (gen + 1u) * nloc) {
;             __builtin_amdgcn_fence(__ATOMIC_RELEASE, "agent");
;             asm volatile("s_waitcnt vmcnt(0)" ::: "memory");
;             const unsigned og = xb_add(&bar[XB_TOP], 1u);
;             const unsigned tg = og / nx;
;             if (og + 1u == (tg + 1u) * nx) xb_add(&bar[XB_TOPGEN], 1u);
;             else XB_SPIN(xb_ld(&bar[XB_TOPGEN]) == tg, bar);
.LBB0_686:
	v_readlane_b32 s0, v254, 13
	v_readlane_b32 s1, v254, 14
	s_and_b64 vcc, exec, s[0:1]
	s_cbranch_vccnz .LBB0_738
	s_waitcnt vmcnt(0)
	s_cmp_gt_u32 s79, 63
	s_waitcnt vmcnt(0) lgkmcnt(0)
	s_barrier
	s_cbranch_scc1 .LBB0_737
	v_mbcnt_lo_u32_b32 v0, -1, 0
	v_mbcnt_hi_u32_b32 v0, -1, v0
	s_nop 0
	v_cmp_eq_u32_e32 vcc, 0, v0
	s_and_saveexec_b64 s[0:1], vcc
	s_cbranch_execz .LBB0_736
	v_readlane_b32 s2, v254, 9
	s_waitcnt vmcnt(0) expcnt(0) lgkmcnt(0)
	s_nop 0
	v_mov_b32_e32 v0, s2
	ds_read_b32 v2, v0
	ds_read_b32 v3, v0 offset:4
	ds_read_b32 v4, v0 offset:8
	ds_read_b32 v5, v0 offset:12
	v_readlane_b32 s2, v254, 8
	s_lshl_b32 s2, s2, 8
	v_readlane_b32 s4, v254, 6
	v_readlane_b32 s5, v254, 7
	s_add_u32 s2, s4, s2
	s_addc_u32 s3, s5, 0
	v_mov_b32_e32 v1, 0x1000
	v_mov_b32_e32 v6, 1
	global_atomic_add v7, v1, v6, s[2:3] offset:1024 sc0
	s_waitcnt lgkmcnt(0)
	v_add_u32_e32 v6, 1, v4
	ds_write_b32 v0, v6 offset:8
	v_add_u32_e32 v4, 2, v4
	v_mul_lo_u32 v2, v2, v4
	v_mul_lo_u32 v3, v3, v4
	s_add_u32 s10, s86, 0x7400
	s_addc_u32 s11, s87, 0
	s_mov_b32 s4, 0x200000
	s_waitcnt vmcnt(0)
	v_add_u32_e32 v7, 1, v7
	v_cmp_ne_u32_e32 vcc, v7, v2
	s_cbranch_vccnz .Lxb2_wait

; __device__ __forceinline__ int lane_id_asm() { int l; asm volatile("v_mbcnt_lo_u32_b32 %0, -1, 0\n\tv_mbcnt_hi_u32_b32 %0, -1, %0" : "=v"(l)); return l; }
; __device__ __forceinline__ unsigned xb_ld(unsigned* p)              { return __hip_atomic_load(p, __ATOMIC_RELAXED, __HIP_MEMORY_SCOPE_AGENT); }
; __device__ __forceinline__ unsigned xb_add(unsigned* p, unsigned v) { return __hip_atomic_fetch_add(p, v, __ATOMIC_RELAXED, __HIP_MEMORY_SCOPE_AGENT); }
; #define XB_SPIN(cond, bar) do { unsigned _sp = 0; while (cond) { __builtin_amdgcn_s_sleep(1); \
;     if ((++_sp & 255u) == 0u) { if (xb_ld(&(bar)[XB_TMO])) break; if (_sp > XB_SPIN_CAP) { atomicAdd(&(bar)[XB_TMO], 1u); break; } } } } while (0)
; __device__ __forceinline__ void xcd_barrier(const XcdBarrier& b, const int wid) {
;     asm volatile("s_waitcnt vmcnt(0)" ::: "memory");
;     __syncthreads();
;     if (wid == 0 && lane_id_asm() == 0) {
;         unsigned* bar = b.bar;
;         __builtin_amdgcn_s_waitcnt(0);
;         unsigned nloc = b.st[0], nx = b.st[1];
;         if (nloc == 0u) { xcd_barrier_complete(bar, b.x, nloc, nx); b.st[0] = nloc; b.st[1] = nx; }
;         const unsigned old = xb_add(&bar[XB_XSUB(b.x)], 1u);
;         const unsigned gen = old / nloc;
;         if (old + 1u == (gen + 1u) * nloc) {
;             __builtin_amdgcn_fence(__ATOMIC_RELEASE, "agent");
;             asm volatile("s_waitcnt vmcnt(0)" ::: "memory");
;             const unsigned og = xb_add(&bar[XB_TOP], 1u);
;             const unsigned tg = og / nx;
;             if (og + 1u == (tg + 1u) * nx) xb_add(&bar[XB_TOPGEN], 1u);
;             else XB_SPIN(xb_ld(&bar[XB_TOPGEN]) == tg, bar);
.LBB0_820:
	v_readlane_b32 s0, v254, 13
	v_readlane_b32 s1, v254, 14
	s_and_b64 vcc, exec, s[0:1]
	s_cbranch_vccnz .LBB0_872
	s_waitcnt vmcnt(0)
	s_cmp_gt_u32 s79, 63
	s_waitcnt vmcnt(0)
	s_barrier
	s_cbranch_scc1 .LBB0_871
	v_mbcnt_lo_u32_b32 v0, -1, 0
	v_mbcnt_hi_u32_b32 v0, -1, v0
	s_nop 0
	v_cmp_eq_u32_e32 vcc, 0, v0
	s_and_saveexec_b64 s[0:1], vcc
	s_cbranch_execz .LBB0_870
	v_readlane_b32 s2, v254, 9
	s_waitcnt vmcnt(0) expcnt(0) lgkmcnt(0)
	s_nop 0
	v_mov_b32_e32 v0, s2
	ds_read_b32 v2, v0
	ds_read_b32 v3, v0 offset:4
	ds_read_b32 v4, v0 offset:8
	ds_read_b32 v5, v0 offset:12
	v_readlane_b32 s2, v254, 8
	s_lshl_b32 s2, s2, 8
	v_readlane_b32 s4, v254, 6
	v_readlane_b32 s5, v254, 7
	s_add_u32 s2, s4, s2
	s_addc_u32 s3, s5, 0
	v_mov_b32_e32 v1, 0x1000
	v_mov_b32_e32 v6, 1
	global_atomic_add v7, v1, v6, s[2:3] offset:1024 sc0
	s_waitcnt lgkmcnt(0)
	v_add_u32_e32 v6, 1, v4
	ds_write_b32 v0, v6 offset:8
	v_add_u32_e32 v4, 2, v4
	v_mul_lo_u32 v2, v2, v4
	v_mul_lo_u32 v3, v3, v4
	s_add_u32 s10, s86, 0x7400
	s_addc_u32 s11, s87, 0
	s_mov_b32 s4, 0x200000
	s_waitcnt vmcnt(0)
	v_add_u32_e32 v7, 1, v7
	v_cmp_ne_u32_e32 vcc, v7, v2
	s_cbranch_vccnz .Lxb3_wait

; __device__ __forceinline__ int lane_id_asm() { int l; asm volatile("v_mbcnt_lo_u32_b32 %0, -1, 0\n\tv_mbcnt_hi_u32_b32 %0, -1, %0" : "=v"(l)); return l; }
; __device__ __forceinline__ unsigned xb_ld(unsigned* p)              { return __hip_atomic_load(p, __ATOMIC_RELAXED, __HIP_MEMORY_SCOPE_AGENT); }
; __device__ __forceinline__ unsigned xb_add(unsigned* p, unsigned v) { return __hip_atomic_fetch_add(p, v, __ATOMIC_RELAXED, __HIP_MEMORY_SCOPE_AGENT); }
; #define XB_SPIN(cond, bar) do { unsigned _sp = 0; while (cond) { __builtin_amdgcn_s_sleep(1); \
;     if ((++_sp & 255u) == 0u) { if (xb_ld(&(bar)[XB_TMO])) break; if (_sp > XB_SPIN_CAP) { atomicAdd(&(bar)[XB_TMO], 1u); break; } } } } while (0)
; __device__ __forceinline__ void xcd_barrier(const XcdBarrier& b, const int wid) {
;     asm volatile("s_waitcnt vmcnt(0)" ::: "memory");
;     __syncthreads();
;     if (wid == 0 && lane_id_asm() == 0) {
;         unsigned* bar = b.bar;
;         __builtin_amdgcn_s_waitcnt(0);
;         unsigned nloc = b.st[0], nx = b.st[1];
;         if (nloc == 0u) { xcd_barrier_complete(bar, b.x, nloc, nx); b.st[0] = nloc; b.st[1] = nx; }
;         const unsigned old = xb_add(&bar[XB_XSUB(b.x)], 1u);
;         const unsigned gen = old / nloc;
;         if (old + 1u == (gen + 1u) * nloc) {
;             __builtin_amdgcn_fence(__ATOMIC_RELEASE, "agent");
;             asm volatile("s_waitcnt vmcnt(0)" ::: "memory");
;             const unsigned og = xb_add(&bar[XB_TOP], 1u);
;             const unsigned tg = og / nx;
;             if (og + 1u == (tg + 1u) * nx) xb_add(&bar[XB_TOPGEN], 1u);
;             else XB_SPIN(xb_ld(&bar[XB_TOPGEN]) == tg, bar);
.LBB0_1476:
	s_and_b64 vcc, exec, s[60:61]
	s_cbranch_vccnz .LBB0_1528
	s_waitcnt vmcnt(0)
	s_cmp_gt_u32 s79, 63
	s_waitcnt vmcnt(0) lgkmcnt(0)
	s_barrier
	s_cbranch_scc1 .LBB0_1527
	v_mbcnt_lo_u32_b32 v0, -1, 0
	v_mbcnt_hi_u32_b32 v0, -1, v0
	s_nop 0
	v_cmp_eq_u32_e32 vcc, 0, v0
	s_and_saveexec_b64 s[0:1], vcc
	s_cbranch_execz .LBB0_1526
	v_readlane_b32 s2, v254, 9
	s_waitcnt vmcnt(0) expcnt(0) lgkmcnt(0)
	s_nop 0
	v_mov_b32_e32 v0, s2
	ds_read_b32 v2, v0
	ds_read_b32 v3, v0 offset:4
	ds_read_b32 v4, v0 offset:8
	ds_read_b32 v5, v0 offset:12
	v_readlane_b32 s2, v254, 8
	s_lshl_b32 s2, s2, 8
	v_readlane_b32 s4, v254, 6
	v_readlane_b32 s5, v254, 7
	s_add_u32 s2, s4, s2
	s_addc_u32 s3, s5, 0
	v_mov_b32_e32 v1, 0x1000
	v_mov_b32_e32 v6, 1
	global_atomic_add v7, v1, v6, s[2:3] offset:1024 sc0
	s_waitcnt lgkmcnt(0)
	v_add_u32_e32 v6, 1, v4
	ds_write_b32 v0, v6 offset:8
	v_add_u32_e32 v4, 2, v4
	v_mul_lo_u32 v2, v2, v4
	v_mul_lo_u32 v3, v3, v4
	s_add_u32 s10, s86, 0x7400
	s_addc_u32 s11, s87, 0
	s_mov_b32 s4, 0x200000
	s_waitcnt vmcnt(0)
	v_add_u32_e32 v7, 1, v7
	v_cmp_ne_u32_e32 vcc, v7, v2
	s_cbranch_vccnz .Lxb5_wait

; __device__ __forceinline__ int lane_id_asm() { int l; asm volatile("v_mbcnt_lo_u32_b32 %0, -1, 0\n\tv_mbcnt_hi_u32_b32 %0, -1, %0" : "=v"(l)); return l; }
; __device__ __forceinline__ unsigned xb_ld(unsigned* p)              { return __hip_atomic_load(p, __ATOMIC_RELAXED, __HIP_MEMORY_SCOPE_AGENT); }
; __device__ __forceinline__ unsigned xb_add(unsigned* p, unsigned v) { return __hip_atomic_fetch_add(p, v, __ATOMIC_RELAXED, __HIP_MEMORY_SCOPE_AGENT); }
; #define XB_SPIN(cond, bar) do { unsigned _sp = 0; while (cond) { __builtin_amdgcn_s_sleep(1); \
;     if ((++_sp & 255u) == 0u) { if (xb_ld(&(bar)[XB_TMO])) break; if (_sp > XB_SPIN_CAP) { atomicAdd(&(bar)[XB_TMO], 1u); break; } } } } while (0)
; __device__ __forceinline__ void xcd_barrier(const XcdBarrier& b, const int wid) {
;     asm volatile("s_waitcnt vmcnt(0)" ::: "memory");
;     __syncthreads();
;     if (wid == 0 && lane_id_asm() == 0) {
;         unsigned* bar = b.bar;
;         __builtin_amdgcn_s_waitcnt(0);
;         unsigned nloc = b.st[0], nx = b.st[1];
;         if (nloc == 0u) { xcd_barrier_complete(bar, b.x, nloc, nx); b.st[0] = nloc; b.st[1] = nx; }
;         const unsigned old = xb_add(&bar[XB_XSUB(b.x)], 1u);
;         const unsigned gen = old / nloc;
;         if (old + 1u == (gen + 1u) * nloc) {
;             __builtin_amdgcn_fence(__ATOMIC_RELEASE, "agent");
;             asm volatile("s_waitcnt vmcnt(0)" ::: "memory");
;             const unsigned og = xb_add(&bar[XB_TOP], 1u);
;             const unsigned tg = og / nx;
;             if (og + 1u == (tg + 1u) * nx) xb_add(&bar[XB_TOPGEN], 1u);
;             else XB_SPIN(xb_ld(&bar[XB_TOPGEN]) == tg, bar);
.LBB0_1621:
	s_and_b64 vcc, exec, s[60:61]
	s_cbranch_vccnz .LBB0_1673
	s_waitcnt vmcnt(0)
	s_cmp_gt_u32 s79, 63
	s_waitcnt vmcnt(0)
	s_barrier
	s_cbranch_scc1 .LBB0_1672
	v_mbcnt_lo_u32_b32 v0, -1, 0
	v_mbcnt_hi_u32_b32 v0, -1, v0
	s_nop 0
	v_cmp_eq_u32_e32 vcc, 0, v0
	s_and_saveexec_b64 s[0:1], vcc
	s_cbranch_execz .LBB0_1671
	v_readlane_b32 s2, v254, 9
	s_waitcnt vmcnt(0) expcnt(0) lgkmcnt(0)
	s_nop 0
	v_mov_b32_e32 v0, s2
	ds_read_b32 v2, v0
	ds_read_b32 v3, v0 offset:4
	ds_read_b32 v4, v0 offset:8
	ds_read_b32 v5, v0 offset:12
	v_readlane_b32 s2, v254, 8
	s_lshl_b32 s2, s2, 8
	v_readlane_b32 s4, v254, 6
	v_readlane_b32 s5, v254, 7
	s_add_u32 s2, s4, s2
	s_addc_u32 s3, s5, 0
	v_mov_b32_e32 v1, 0x1000
	v_mov_b32_e32 v6, 1
	global_atomic_add v7, v1, v6, s[2:3] offset:1024 sc0
	s_waitcnt lgkmcnt(0)
	v_add_u32_e32 v6, 1, v4
	ds_write_b32 v0, v6 offset:8
	v_add_u32_e32 v4, 2, v4
	v_mul_lo_u32 v2, v2, v4
	v_mul_lo_u32 v3, v3, v4
	s_add_u32 s10, s86, 0x7400
	s_addc_u32 s11, s87, 0
	s_mov_b32 s4, 0x200000
	s_waitcnt vmcnt(0)
	v_add_u32_e32 v7, 1, v7
	v_cmp_ne_u32_e32 vcc, v7, v2
	s_cbranch_vccnz .Lxb6_wait
